# attention unit prologue: tiles 0-2 loads issued together with counted waits (was load/wait/store per tile), on top of v22
# baseline (speedup 1.0000x reference)
; #define ATT_LOAD(t) do { sk0 = *(const u32x4*)(kp0 + (size_t)(t) * 64 * 768); if (has1) sk1 = *(const u32x4*)(kp1 + (size_t)(t) * 64 * 768); sv = *(const u32x4*)(vp + (t) * 64); } while (0)
; #define ATT_STORE(boff) do { *(LAS u32x4*)(lds + (boff) + kw0) = sk0; if (has1) *(LAS u32x4*)(lds + (boff) + kw1) = sk1; *(LAS u32x4*)(lds + (boff) + vw) = sv; } while (0)
; template <bool FIXED> __device__ __forceinline__ void attn_unit(unsigned char* ws, LAS unsigned char* lds, int b, int h, int qb, const int tid, const float sbound) {
;     ...
;     ATT_LOAD(0); ATT_STORE(0); ATT_LOAD(1); ATT_STORE(ABUF); ATT_LOAD(2);
;     __syncthreads();
;     const int pi_r = (r32 & ~12) | ((r32 & 4) << 1) | ((r32 & 8) >> 1);
;     const int kro = pi_r * AKP + hi * 16, vro = AKB + r32 * AVP + hi * 16;
;     f32x16 o0 = {}, o1 = {}, negm = {};
;     float mref = 0.f, lsum = 0.f;
.LBB0_745:
	s_ashr_i32 s14, s16, 8
	s_ashr_i32 s15, s14, 31
	s_lshl_b32 s3, s16, 8
	s_lshl_b64 s[38:39], s[14:15], 13
	s_and_b32 s3, s3, 0x1f00
	v_readlane_b32 s6, v253, 51
	s_or_b32 s38, s38, s3
	v_readlane_b32 s7, v253, 52
	v_lshl_add_u64 v[216:217], s[38:39], 0, v[194:195]
	s_movk_i32 s3, 0x600
	v_mov_b64_e32 v[16:17], s[6:7]
	v_mad_u64_u32 v[16:17], s[38:39], v216, s3, v[16:17]
	v_mov_b32_e32 v18, v17
	s_bfe_u32 s17, s16, 0x30005
	v_mad_u64_u32 v[18:19], s[38:39], v217, s3, v[18:19]
	s_mul_i32 s88, s17, 0xc0
	v_mov_b32_e32 v17, v18
	s_mul_i32 s47, s14, 0xc00000
	v_lshl_add_u64 v[16:17], v[16:17], 0, s[88:89]
	s_mul_hi_i32 s46, s14, 0xc00000
	s_add_u32 s3, s51, s47
	v_readlane_b32 s6, v254, 9
	v_lshl_add_u64 v[16:17], v[16:17], 0, v[184:185]
	s_addc_u32 s6, s6, s46
	global_load_dwordx4 v[144:147], v[16:17], off offset:32
	global_load_dwordx4 v[148:151], v[16:17], off offset:64
	global_load_dwordx4 v[152:155], v[16:17], off offset:96
	global_load_dwordx4 v[156:159], v[16:17], off offset:128
	global_load_dwordx4 v[160:163], v[16:17], off offset:160
	s_add_u32 s38, s3, s88
	s_addc_u32 s39, s6, 0
	v_lshl_add_u64 v[18:19], s[38:39], 0, v[196:197]
	v_lshl_add_u64 v[222:223], v[198:199], 1, v[18:19]
	global_load_dwordx4 v[164:167], v[16:17], off
	global_load_dwordx4 v[168:171], v[222:223], off
	s_lshl_b32 s50, s14, 3
	s_or_b32 s14, s50, s17
	s_ashr_i32 s15, s14, 31
	s_lshl_b64 s[14:15], s[14:15], 20
	v_lshl_add_u64 v[16:17], s[38:39], 0, v[200:201]
	v_lshl_add_u64 v[220:221], v[202:203], 1, v[16:17]
	v_lshl_add_u64 v[218:219], v[206:207], 0, s[14:15]
	s_andn2_b64 vcc, exec, s[34:35]
	s_mov_b64 s[38:39], -1
	s_cbranch_vccnz .LBB0_777
	s_waitcnt vmcnt(16)
	v_mov_b32_e32 v172, v185
	v_mov_b32_e32 v173, v185
	v_mov_b32_e32 v174, v185
	v_mov_b32_e32 v175, v185
	v_add_co_u32_e32 v36, vcc, 0x18000, v222
	s_nop 1
	v_addc_co_u32_e32 v37, vcc, 0, v223, vcc
	v_add_co_u32_e32 v40, vcc, 0x30000, v222
	s_nop 1
	v_addc_co_u32_e32 v41, vcc, 0, v223, vcc
	v_add_co_u32_e32 v38, vcc, 0x18000, v220
	s_nop 1
	v_addc_co_u32_e32 v39, vcc, 0, v221, vcc
	v_add_co_u32_e32 v42, vcc, 0x30000, v220
	s_nop 1
	v_addc_co_u32_e32 v43, vcc, 0, v221, vcc
	s_and_saveexec_b64 s[38:39], s[36:37]
	s_cbranch_execz .Lattn_pro_a
	global_load_dwordx4 v[28:31], v[220:221], off
.Lattn_pro_a:
	s_or_b64 exec, exec, s[38:39]
	global_load_dwordx4 v[16:19], v[218:219], off
	global_load_dwordx4 v[20:23], v[36:37], off
	s_and_saveexec_b64 s[38:39], s[36:37]
	s_cbranch_execz .Lattn_pro_b
	global_load_dwordx4 v[32:35], v[38:39], off
.Lattn_pro_b:
	s_or_b64 exec, exec, s[38:39]
	global_load_dwordx4 v[24:27], v[218:219], off offset:128
	global_load_dwordx4 v[176:179], v[40:41], off
	s_and_saveexec_b64 s[38:39], s[36:37]
	s_cbranch_execz .Lattn_pro_c
	global_load_dwordx4 v[172:175], v[42:43], off
.Lattn_pro_c:
	s_or_b64 exec, exec, s[38:39]
	global_load_dwordx4 v[180:183], v[218:219], off offset:256
	s_waitcnt vmcnt(4)
	ds_write_b128 v211, v[168:171]
	s_and_saveexec_b64 s[38:39], s[36:37]
	s_cbranch_execz .Lattn_pro_d
	ds_write_b128 v186, v[28:31]
.Lattn_pro_d:
	s_or_b64 exec, exec, s[38:39]
	ds_write_b128 v208, v[16:19] offset:13312
	s_waitcnt vmcnt(2)
	ds_write_b128 v211, v[20:23] offset:22528
	s_and_saveexec_b64 s[38:39], s[36:37]
	s_cbranch_execz .Lattn_pro_e
	ds_write_b128 v186, v[32:35] offset:22528
.Lattn_pro_e:
	s_or_b64 exec, exec, s[38:39]
	ds_write_b128 v208, v[24:27] offset:35840
	s_waitcnt lgkmcnt(0)
	s_barrier
	ds_read_b128 v[16:19], v187 offset:6656
	ds_read_b128 v[20:23], v187
	ds_read_b128 v[24:27], v187 offset:32
	ds_read_b128 v[28:31], v187 offset:6688
	ds_read_b128 v[32:35], v187 offset:64
	ds_read_b128 v[36:39], v187 offset:6720
	ds_read_b128 v[40:43], v187 offset:96
	ds_read_b128 v[44:47], v187 offset:6752
	ds_read_b128 v[80:83], v187 offset:128
	ds_read_b128 v[84:87], v187 offset:6784
	ds_read_b128 v[88:91], v187 offset:160
	ds_read_b128 v[92:95], v187 offset:6816
	s_waitcnt lgkmcnt(10)
	v_mfma_f32_32x32x16_bf16 v[64:79], v[20:23], v[164:167], v[0:15]
	s_add_i32 s14, s50, s17
	s_ashr_i32 s15, s14, 31
	s_lshl_b64 s[14:15], s[14:15], 20
	v_lshl_add_u64 v[224:225], v[204:205], 0, s[14:15]
	s_add_u32 s14, s88, s47
	s_addc_u32 s15, 0, s46
	v_lshl_add_u64 v[226:227], s[14:15], 0, v[212:213]
	v_mfma_f32_32x32x16_bf16 v[48:63], v[16:19], v[164:167], v[0:15]
	v_mov_b32_e32 v16, 0
	v_lshl_add_u64 v[228:229], s[14:15], 0, v[214:215]
	s_mov_b32 s14, 0
	v_mov_b32_e32 v17, v16
	v_mov_b32_e32 v18, v16
	v_mov_b32_e32 v19, v16
	v_mov_b32_e32 v20, v16
	s_waitcnt lgkmcnt(9)
	v_mfma_f32_32x32x16_bf16 v[64:79], v[24:27], v[144:147], v[64:79]
	v_mov_b32_e32 v21, v16
	v_mov_b32_e32 v22, v16
	v_mov_b32_e32 v23, v16
	v_mov_b32_e32 v24, v16
	v_mov_b32_e32 v25, v16
	v_mov_b32_e32 v26, v16
	v_mov_b32_e32 v27, v16
	s_waitcnt lgkmcnt(8)
	v_mfma_f32_32x32x16_bf16 v[48:63], v[28:31], v[144:147], v[48:63]
	v_mov_b32_e32 v28, v16
	v_mov_b32_e32 v29, v16
	v_mov_b32_e32 v30, v16
	v_mov_b32_e32 v31, v16
	v_mov_b32_e32 v244, v16
	v_mov_b32_e32 v245, v16
	v_mov_b32_e32 v242, v16
	s_waitcnt lgkmcnt(7)
	v_mfma_f32_32x32x16_bf16 v[64:79], v[32:35], v[148:151], v[64:79]
	v_mov_b32_e32 v32, v16
	v_mov_b32_e32 v33, v16
	v_mov_b32_e32 v34, v16
	v_mov_b32_e32 v35, v16
	v_mov_b32_e32 v243, v16
	v_mov_b32_e32 v240, v16
	v_mov_b32_e32 v241, v16
	s_waitcnt lgkmcnt(6)
	v_mfma_f32_32x32x16_bf16 v[48:63], v[36:39], v[148:151], v[48:63]
	v_mov_b32_e32 v36, v16
	v_mov_b32_e32 v37, v16
	v_mov_b32_e32 v38, v16
	v_mov_b32_e32 v39, v16
	v_mov_b32_e32 v238, v16
	v_mov_b32_e32 v239, v16
	v_mov_b32_e32 v236, v16
	s_waitcnt lgkmcnt(5)
	v_mfma_f32_32x32x16_bf16 v[64:79], v[40:43], v[152:155], v[64:79]
	v_mov_b32_e32 v40, v16
	v_mov_b32_e32 v41, v16
	v_mov_b32_e32 v42, v16
	v_mov_b32_e32 v43, v16
	v_mov_b32_e32 v237, v16
	v_mov_b32_e32 v234, v16
	v_mov_b32_e32 v235, v16
	s_waitcnt lgkmcnt(4)
	v_mfma_f32_32x32x16_bf16 v[48:63], v[44:47], v[152:155], v[48:63]
	v_mov_b32_e32 v44, v16
	v_mov_b32_e32 v45, v16
	v_mov_b32_e32 v46, v16
	v_mov_b32_e32 v47, v16
	v_mov_b32_e32 v232, v16
	v_mov_b32_e32 v233, v16
	v_mov_b32_e32 v230, v16
	s_waitcnt lgkmcnt(3)
	v_mfma_f32_32x32x16_bf16 v[64:79], v[80:83], v[156:159], v[64:79]
	v_mov_b32_e32 v231, v16
	s_waitcnt lgkmcnt(2)
	v_mfma_f32_32x32x16_bf16 v[48:63], v[84:87], v[156:159], v[48:63]
	s_waitcnt lgkmcnt(1)
	v_mfma_f32_32x32x16_bf16 v[64:79], v[88:91], v[160:163], v[64:79]
	s_waitcnt lgkmcnt(0)
	v_mfma_f32_32x32x16_bf16 v[48:63], v[92:95], v[160:163], v[48:63]
	s_branch .LBB0_758
